# final LayerNorm pass: output stores marked non-temporal (write-once stream)
# baseline (speedup 1.0000x reference)
.Lln2_loop:
	global_load_dwordx4 v[108:111], v[232:233], off
	global_load_dwordx4 v[112:115], v[232:233], off offset:1024
	global_load_dwordx4 v[116:119], v[234:235], off
	global_load_dwordx4 v[120:123], v[234:235], off offset:1024
	global_load_dwordx2 v[124:125], v[236:237], off
	s_cmp_lt_u32 s33, 28
	s_cselect_b32 s44, s40, 0
	s_cselect_b32 s46, s42, 0
	s_mov_b32 s45, 0
	s_mov_b32 s47, 0
	v_lshl_add_u64 v[232:233], v[232:233], 0, s[44:45]
	v_lshl_add_u64 v[234:235], v[234:235], 0, s[44:45]
	v_lshl_add_u64 v[236:237], v[236:237], 0, s[46:47]
	s_waitcnt vmcnt(18)
	v_lshlrev_b32_e32 v16, 16, v56
	v_and_b32_e32 v17, 0xffff0000, v56
	v_lshlrev_b32_e32 v0, 16, v48
	v_and_b32_e32 v1, 0xffff0000, v48
	v_sub_f32_e32 v16, v16, v64
	v_sub_f32_e32 v17, v17, v64
	v_mul_f32_e32 v16, v16, v65
	v_mul_f32_e32 v17, v17, v65
	v_fma_f32 v16, v16, v128, v144
	v_fma_f32 v17, v17, v129, v145
	v_fma_f32 v0, v16, s14, v0
	v_fma_f32 v1, v17, s14, v1
	v_lshlrev_b32_e32 v18, 16, v57
	v_and_b32_e32 v19, 0xffff0000, v57
	v_lshlrev_b32_e32 v2, 16, v49
	v_and_b32_e32 v3, 0xffff0000, v49
	v_sub_f32_e32 v18, v18, v64
	v_sub_f32_e32 v19, v19, v64
	v_mul_f32_e32 v18, v18, v65
	v_mul_f32_e32 v19, v19, v65
	v_fma_f32 v18, v18, v130, v146
	v_fma_f32 v19, v19, v131, v147
	v_fma_f32 v2, v18, s14, v2
	v_fma_f32 v3, v19, s14, v3
	v_lshlrev_b32_e32 v20, 16, v58
	v_and_b32_e32 v21, 0xffff0000, v58
	v_lshlrev_b32_e32 v4, 16, v50
	v_and_b32_e32 v5, 0xffff0000, v50
	v_sub_f32_e32 v20, v20, v64
	v_sub_f32_e32 v21, v21, v64
	v_mul_f32_e32 v20, v20, v65
	v_mul_f32_e32 v21, v21, v65
	v_fma_f32 v20, v20, v132, v148
	v_fma_f32 v21, v21, v133, v149
	v_fma_f32 v4, v20, s14, v4
	v_fma_f32 v5, v21, s14, v5
	v_lshlrev_b32_e32 v22, 16, v59
	v_and_b32_e32 v23, 0xffff0000, v59
	v_lshlrev_b32_e32 v6, 16, v51
	v_and_b32_e32 v7, 0xffff0000, v51
	v_sub_f32_e32 v22, v22, v64
	v_sub_f32_e32 v23, v23, v64
	v_mul_f32_e32 v22, v22, v65
	v_mul_f32_e32 v23, v23, v65
	v_fma_f32 v22, v22, v134, v150
	v_fma_f32 v23, v23, v135, v151
	v_fma_f32 v6, v22, s14, v6
	v_fma_f32 v7, v23, s14, v7
	v_lshlrev_b32_e32 v24, 16, v60
	v_and_b32_e32 v25, 0xffff0000, v60
	v_lshlrev_b32_e32 v8, 16, v52
	v_and_b32_e32 v9, 0xffff0000, v52
	v_sub_f32_e32 v24, v24, v64
	v_sub_f32_e32 v25, v25, v64
	v_mul_f32_e32 v24, v24, v65
	v_mul_f32_e32 v25, v25, v65
	v_fma_f32 v24, v24, v136, v152
	v_fma_f32 v25, v25, v137, v153
	v_fma_f32 v8, v24, s14, v8
	v_fma_f32 v9, v25, s14, v9
	v_lshlrev_b32_e32 v26, 16, v61
	v_and_b32_e32 v27, 0xffff0000, v61
	v_lshlrev_b32_e32 v10, 16, v53
	v_and_b32_e32 v11, 0xffff0000, v53
	v_sub_f32_e32 v26, v26, v64
	v_sub_f32_e32 v27, v27, v64
	v_mul_f32_e32 v26, v26, v65
	v_mul_f32_e32 v27, v27, v65
	v_fma_f32 v26, v26, v138, v154
	v_fma_f32 v27, v27, v139, v155
	v_fma_f32 v10, v26, s14, v10
	v_fma_f32 v11, v27, s14, v11
	v_lshlrev_b32_e32 v28, 16, v62
	v_and_b32_e32 v29, 0xffff0000, v62
	v_lshlrev_b32_e32 v12, 16, v54
	v_and_b32_e32 v13, 0xffff0000, v54
	v_sub_f32_e32 v28, v28, v64
	v_sub_f32_e32 v29, v29, v64
	v_mul_f32_e32 v28, v28, v65
	v_mul_f32_e32 v29, v29, v65
	v_fma_f32 v28, v28, v140, v156
	v_fma_f32 v29, v29, v141, v157
	v_fma_f32 v12, v28, s14, v12
	v_fma_f32 v13, v29, s14, v13
	v_lshlrev_b32_e32 v30, 16, v63
	v_and_b32_e32 v31, 0xffff0000, v63
	v_lshlrev_b32_e32 v14, 16, v55
	v_and_b32_e32 v15, 0xffff0000, v55
	v_sub_f32_e32 v30, v30, v64
	v_sub_f32_e32 v31, v31, v64
	v_mul_f32_e32 v30, v30, v65
	v_mul_f32_e32 v31, v31, v65
	v_fma_f32 v30, v30, v142, v158
	v_fma_f32 v31, v31, v143, v159
	v_fma_f32 v14, v30, s14, v14
	v_fma_f32 v15, v31, s14, v15
	v_add_f32_e32 v16, v0, v1
	v_add_f32_e32 v17, v2, v3
	v_add_f32_e32 v18, v4, v5
	v_add_f32_e32 v19, v6, v7
	v_add_f32_e32 v20, v8, v9
	v_add_f32_e32 v21, v10, v11
	v_add_f32_e32 v22, v12, v13
	v_add_f32_e32 v23, v14, v15
	v_add_f32_e32 v16, v16, v17
	v_add_f32_e32 v18, v18, v19
	v_add_f32_e32 v20, v20, v21
	v_add_f32_e32 v22, v22, v23
	v_add_f32_e32 v16, v16, v18
	v_add_f32_e32 v20, v20, v22
	v_add_f32_e32 v32, v16, v20
	v_mov_b32_e32 v34, v32
	s_nop 1
	v_add_f32_dpp v34, v32, v32 quad_perm:[1,0,3,2] row_mask:0xf bank_mask:0xf
	s_nop 1
	v_add_f32_dpp v34, v34, v34 quad_perm:[2,3,0,1] row_mask:0xf bank_mask:0xf
	s_nop 1
	v_add_f32_dpp v34, v34, v34 row_half_mirror row_mask:0xf bank_mask:0xf
	s_nop 1
	v_add_f32_dpp v34, v34, v34 row_mirror row_mask:0xf bank_mask:0xf
	s_nop 1
	v_add_f32_dpp v34, v34, v34 row_bcast:15 row_mask:0xa bank_mask:0xf
	s_nop 1
	v_add_f32_dpp v34, v34, v34 row_bcast:31 row_mask:0xc bank_mask:0xf
	s_nop 1
	v_readlane_b32 s0, v34, 63
	s_nop 0
	v_mov_b32_e32 v33, 0x3a800000
	v_mul_f32_e32 v33, s0, v33
	v_sub_f32_e32 v0, v0, v33
	v_sub_f32_e32 v1, v1, v33
	v_sub_f32_e32 v2, v2, v33
	v_sub_f32_e32 v3, v3, v33
	v_sub_f32_e32 v4, v4, v33
	v_sub_f32_e32 v5, v5, v33
	v_sub_f32_e32 v6, v6, v33
	v_sub_f32_e32 v7, v7, v33
	v_sub_f32_e32 v8, v8, v33
	v_sub_f32_e32 v9, v9, v33
	v_sub_f32_e32 v10, v10, v33
	v_sub_f32_e32 v11, v11, v33
	v_sub_f32_e32 v12, v12, v33
	v_sub_f32_e32 v13, v13, v33
	v_sub_f32_e32 v14, v14, v33
	v_sub_f32_e32 v15, v15, v33
	v_mul_f32_e32 v16, v0, v0
	v_fmac_f32_e32 v16, v1, v1
	v_mul_f32_e32 v17, v2, v2
	v_fmac_f32_e32 v17, v3, v3
	v_mul_f32_e32 v18, v4, v4
	v_fmac_f32_e32 v18, v5, v5
	v_mul_f32_e32 v19, v6, v6
	v_fmac_f32_e32 v19, v7, v7
	v_mul_f32_e32 v20, v8, v8
	v_fmac_f32_e32 v20, v9, v9
	v_mul_f32_e32 v21, v10, v10
	v_fmac_f32_e32 v21, v11, v11
	v_mul_f32_e32 v22, v12, v12
	v_fmac_f32_e32 v22, v13, v13
	v_mul_f32_e32 v23, v14, v14
	v_fmac_f32_e32 v23, v15, v15
	v_add_f32_e32 v16, v16, v17
	v_add_f32_e32 v18, v18, v19
	v_add_f32_e32 v20, v20, v21
	v_add_f32_e32 v22, v22, v23
	v_add_f32_e32 v16, v16, v18
	v_add_f32_e32 v20, v20, v22
	v_add_f32_e32 v32, v16, v20
	v_mov_b32_e32 v34, v32
	s_nop 1
	v_add_f32_dpp v34, v32, v32 quad_perm:[1,0,3,2] row_mask:0xf bank_mask:0xf
	s_nop 1
	v_add_f32_dpp v34, v34, v34 quad_perm:[2,3,0,1] row_mask:0xf bank_mask:0xf
	s_nop 1
	v_add_f32_dpp v34, v34, v34 row_half_mirror row_mask:0xf bank_mask:0xf
	s_nop 1
	v_add_f32_dpp v34, v34, v34 row_mirror row_mask:0xf bank_mask:0xf
	s_nop 1
	v_add_f32_dpp v34, v34, v34 row_bcast:15 row_mask:0xa bank_mask:0xf
	s_nop 1
	v_add_f32_dpp v34, v34, v34 row_bcast:31 row_mask:0xc bank_mask:0xf
	s_nop 1
	v_readlane_b32 s0, v34, 63
	s_nop 0
	v_mov_b32_e32 v33, 0x3a800000
	v_mov_b32_e32 v35, 0x3727c5ac
	v_fma_f32 v33, s0, v33, v35
	v_rsq_f32_e32 v33, v33
	s_nop 0
	v_mul_f32_e32 v0, v0, v33
	v_mul_f32_e32 v1, v1, v33
	v_mul_f32_e32 v2, v2, v33
	v_mul_f32_e32 v3, v3, v33
	v_fma_f32 v0, v0, v160, v176
	v_fma_f32 v1, v1, v161, v177
	v_fma_f32 v2, v2, v162, v178
	v_fma_f32 v3, v3, v163, v179
	v_mul_f32_e32 v4, v4, v33
	v_mul_f32_e32 v5, v5, v33
	v_mul_f32_e32 v6, v6, v33
	v_mul_f32_e32 v7, v7, v33
	v_fma_f32 v4, v4, v164, v180
	v_fma_f32 v5, v5, v165, v181
	v_fma_f32 v6, v6, v166, v182
	v_fma_f32 v7, v7, v167, v183
	v_mul_f32_e32 v8, v8, v33
	v_mul_f32_e32 v9, v9, v33
	v_mul_f32_e32 v10, v10, v33
	v_mul_f32_e32 v11, v11, v33
	v_fma_f32 v8, v8, v168, v184
	v_fma_f32 v9, v9, v169, v185
	v_fma_f32 v10, v10, v170, v186
	v_fma_f32 v11, v11, v171, v187
	v_mul_f32_e32 v12, v12, v33
	v_mul_f32_e32 v13, v13, v33
	v_mul_f32_e32 v14, v14, v33
	v_mul_f32_e32 v15, v15, v33
	v_fma_f32 v12, v12, v172, v188
	v_fma_f32 v13, v13, v173, v189
	v_fma_f32 v14, v14, v174, v190
	v_fma_f32 v15, v15, v175, v191
	global_store_dwordx4 v[238:239], v[0:3], off nt
	global_store_dwordx4 v[238:239], v[4:7], off offset:16 nt
	global_store_dwordx4 v[238:239], v[8:11], off offset:2048 nt
	global_store_dwordx4 v[238:239], v[12:15], off offset:2064 nt
	s_mov_b32 s44, 0x800000
	s_mov_b32 s45, 0
	v_lshl_add_u64 v[238:239], v[238:239], 0, s[44:45]
	s_add_u32 s33, s33, 1
	global_load_dwordx4 v[48:51], v[232:233], off
	global_load_dwordx4 v[52:55], v[232:233], off offset:1024
	global_load_dwordx4 v[56:59], v[234:235], off
	global_load_dwordx4 v[60:63], v[234:235], off offset:1024
	global_load_dwordx2 v[64:65], v[236:237], off
	s_cmp_lt_u32 s33, 28
	s_cselect_b32 s44, s40, 0
	s_cselect_b32 s46, s42, 0
	s_mov_b32 s45, 0
	s_mov_b32 s47, 0
	v_lshl_add_u64 v[232:233], v[232:233], 0, s[44:45]
	v_lshl_add_u64 v[234:235], v[234:235], 0, s[44:45]
	v_lshl_add_u64 v[236:237], v[236:237], 0, s[46:47]
	s_waitcnt vmcnt(18)
	v_lshlrev_b32_e32 v16, 16, v76
	v_and_b32_e32 v17, 0xffff0000, v76
	v_lshlrev_b32_e32 v0, 16, v68
	v_and_b32_e32 v1, 0xffff0000, v68
	v_sub_f32_e32 v16, v16, v84
	v_sub_f32_e32 v17, v17, v84
	v_mul_f32_e32 v16, v16, v85
	v_mul_f32_e32 v17, v17, v85
	v_fma_f32 v16, v16, v128, v144
	v_fma_f32 v17, v17, v129, v145
	v_fma_f32 v0, v16, s14, v0
	v_fma_f32 v1, v17, s14, v1
	v_lshlrev_b32_e32 v18, 16, v77
	v_and_b32_e32 v19, 0xffff0000, v77
	v_lshlrev_b32_e32 v2, 16, v69
	v_and_b32_e32 v3, 0xffff0000, v69
	v_sub_f32_e32 v18, v18, v84
	v_sub_f32_e32 v19, v19, v84
	v_mul_f32_e32 v18, v18, v85
	v_mul_f32_e32 v19, v19, v85
	v_fma_f32 v18, v18, v130, v146
	v_fma_f32 v19, v19, v131, v147
	v_fma_f32 v2, v18, s14, v2
	v_fma_f32 v3, v19, s14, v3
	v_lshlrev_b32_e32 v20, 16, v78
	v_and_b32_e32 v21, 0xffff0000, v78
	v_lshlrev_b32_e32 v4, 16, v70
	v_and_b32_e32 v5, 0xffff0000, v70
	v_sub_f32_e32 v20, v20, v84
	v_sub_f32_e32 v21, v21, v84
	v_mul_f32_e32 v20, v20, v85
	v_mul_f32_e32 v21, v21, v85
	v_fma_f32 v20, v20, v132, v148
	v_fma_f32 v21, v21, v133, v149
	v_fma_f32 v4, v20, s14, v4
	v_fma_f32 v5, v21, s14, v5
	v_lshlrev_b32_e32 v22, 16, v79
	v_and_b32_e32 v23, 0xffff0000, v79
	v_lshlrev_b32_e32 v6, 16, v71
	v_and_b32_e32 v7, 0xffff0000, v71
	v_sub_f32_e32 v22, v22, v84
	v_sub_f32_e32 v23, v23, v84
	v_mul_f32_e32 v22, v22, v85
	v_mul_f32_e32 v23, v23, v85
	v_fma_f32 v22, v22, v134, v150
	v_fma_f32 v23, v23, v135, v151
	v_fma_f32 v6, v22, s14, v6
	v_fma_f32 v7, v23, s14, v7
	v_lshlrev_b32_e32 v24, 16, v80
	v_and_b32_e32 v25, 0xffff0000, v80
	v_lshlrev_b32_e32 v8, 16, v72
	v_and_b32_e32 v9, 0xffff0000, v72
	v_sub_f32_e32 v24, v24, v84
	v_sub_f32_e32 v25, v25, v84
	v_mul_f32_e32 v24, v24, v85
	v_mul_f32_e32 v25, v25, v85
	v_fma_f32 v24, v24, v136, v152
	v_fma_f32 v25, v25, v137, v153
	v_fma_f32 v8, v24, s14, v8
	v_fma_f32 v9, v25, s14, v9
	v_lshlrev_b32_e32 v26, 16, v81
	v_and_b32_e32 v27, 0xffff0000, v81
	v_lshlrev_b32_e32 v10, 16, v73
	v_and_b32_e32 v11, 0xffff0000, v73
	v_sub_f32_e32 v26, v26, v84
	v_sub_f32_e32 v27, v27, v84
	v_mul_f32_e32 v26, v26, v85
	v_mul_f32_e32 v27, v27, v85
	v_fma_f32 v26, v26, v138, v154
	v_fma_f32 v27, v27, v139, v155
	v_fma_f32 v10, v26, s14, v10
	v_fma_f32 v11, v27, s14, v11
	v_lshlrev_b32_e32 v28, 16, v82
	v_and_b32_e32 v29, 0xffff0000, v82
	v_lshlrev_b32_e32 v12, 16, v74
	v_and_b32_e32 v13, 0xffff0000, v74
	v_sub_f32_e32 v28, v28, v84
	v_sub_f32_e32 v29, v29, v84
	v_mul_f32_e32 v28, v28, v85
	v_mul_f32_e32 v29, v29, v85
	v_fma_f32 v28, v28, v140, v156
	v_fma_f32 v29, v29, v141, v157
	v_fma_f32 v12, v28, s14, v12
	v_fma_f32 v13, v29, s14, v13
	v_lshlrev_b32_e32 v30, 16, v83
	v_and_b32_e32 v31, 0xffff0000, v83
	v_lshlrev_b32_e32 v14, 16, v75
	v_and_b32_e32 v15, 0xffff0000, v75
	v_sub_f32_e32 v30, v30, v84
	v_sub_f32_e32 v31, v31, v84
	v_mul_f32_e32 v30, v30, v85
	v_mul_f32_e32 v31, v31, v85
	v_fma_f32 v30, v30, v142, v158
	v_fma_f32 v31, v31, v143, v159
	v_fma_f32 v14, v30, s14, v14
	v_fma_f32 v15, v31, s14, v15
	v_add_f32_e32 v16, v0, v1
	v_add_f32_e32 v17, v2, v3
	v_add_f32_e32 v18, v4, v5
	v_add_f32_e32 v19, v6, v7
	v_add_f32_e32 v20, v8, v9
	v_add_f32_e32 v21, v10, v11
	v_add_f32_e32 v22, v12, v13
	v_add_f32_e32 v23, v14, v15
	v_add_f32_e32 v16, v16, v17
	v_add_f32_e32 v18, v18, v19
	v_add_f32_e32 v20, v20, v21
	v_add_f32_e32 v22, v22, v23
	v_add_f32_e32 v16, v16, v18
	v_add_f32_e32 v20, v20, v22
	v_add_f32_e32 v32, v16, v20
	v_mov_b32_e32 v34, v32
	s_nop 1
	v_add_f32_dpp v34, v32, v32 quad_perm:[1,0,3,2] row_mask:0xf bank_mask:0xf
	s_nop 1
	v_add_f32_dpp v34, v34, v34 quad_perm:[2,3,0,1] row_mask:0xf bank_mask:0xf
	s_nop 1
	v_add_f32_dpp v34, v34, v34 row_half_mirror row_mask:0xf bank_mask:0xf
	s_nop 1
	v_add_f32_dpp v34, v34, v34 row_mirror row_mask:0xf bank_mask:0xf
	s_nop 1
	v_add_f32_dpp v34, v34, v34 row_bcast:15 row_mask:0xa bank_mask:0xf
	s_nop 1
	v_add_f32_dpp v34, v34, v34 row_bcast:31 row_mask:0xc bank_mask:0xf
	s_nop 1
	v_readlane_b32 s0, v34, 63
	s_nop 0
	v_mov_b32_e32 v33, 0x3a800000
	v_mul_f32_e32 v33, s0, v33
	v_sub_f32_e32 v0, v0, v33
	v_sub_f32_e32 v1, v1, v33
	v_sub_f32_e32 v2, v2, v33
	v_sub_f32_e32 v3, v3, v33
	v_sub_f32_e32 v4, v4, v33
	v_sub_f32_e32 v5, v5, v33
	v_sub_f32_e32 v6, v6, v33
	v_sub_f32_e32 v7, v7, v33
	v_sub_f32_e32 v8, v8, v33
	v_sub_f32_e32 v9, v9, v33
	v_sub_f32_e32 v10, v10, v33
	v_sub_f32_e32 v11, v11, v33
	v_sub_f32_e32 v12, v12, v33
	v_sub_f32_e32 v13, v13, v33
	v_sub_f32_e32 v14, v14, v33
	v_sub_f32_e32 v15, v15, v33
	v_mul_f32_e32 v16, v0, v0
	v_fmac_f32_e32 v16, v1, v1
	v_mul_f32_e32 v17, v2, v2
	v_fmac_f32_e32 v17, v3, v3
	v_mul_f32_e32 v18, v4, v4
	v_fmac_f32_e32 v18, v5, v5
	v_mul_f32_e32 v19, v6, v6
	v_fmac_f32_e32 v19, v7, v7
	v_mul_f32_e32 v20, v8, v8
	v_fmac_f32_e32 v20, v9, v9
	v_mul_f32_e32 v21, v10, v10
	v_fmac_f32_e32 v21, v11, v11
	v_mul_f32_e32 v22, v12, v12
	v_fmac_f32_e32 v22, v13, v13
	v_mul_f32_e32 v23, v14, v14
	v_fmac_f32_e32 v23, v15, v15
	v_add_f32_e32 v16, v16, v17
	v_add_f32_e32 v18, v18, v19
	v_add_f32_e32 v20, v20, v21
	v_add_f32_e32 v22, v22, v23
	v_add_f32_e32 v16, v16, v18
	v_add_f32_e32 v20, v20, v22
	v_add_f32_e32 v32, v16, v20
	v_mov_b32_e32 v34, v32
	s_nop 1
	v_add_f32_dpp v34, v32, v32 quad_perm:[1,0,3,2] row_mask:0xf bank_mask:0xf
	s_nop 1
	v_add_f32_dpp v34, v34, v34 quad_perm:[2,3,0,1] row_mask:0xf bank_mask:0xf
	s_nop 1
	v_add_f32_dpp v34, v34, v34 row_half_mirror row_mask:0xf bank_mask:0xf
	s_nop 1
	v_add_f32_dpp v34, v34, v34 row_mirror row_mask:0xf bank_mask:0xf
	s_nop 1
	v_add_f32_dpp v34, v34, v34 row_bcast:15 row_mask:0xa bank_mask:0xf
	s_nop 1
	v_add_f32_dpp v34, v34, v34 row_bcast:31 row_mask:0xc bank_mask:0xf
	s_nop 1
	v_readlane_b32 s0, v34, 63
	s_nop 0
	v_mov_b32_e32 v33, 0x3a800000
	v_mov_b32_e32 v35, 0x3727c5ac
	v_fma_f32 v33, s0, v33, v35
	v_rsq_f32_e32 v33, v33
	s_nop 0
	v_mul_f32_e32 v0, v0, v33
	v_mul_f32_e32 v1, v1, v33
	v_mul_f32_e32 v2, v2, v33
	v_mul_f32_e32 v3, v3, v33
	v_fma_f32 v0, v0, v160, v176
	v_fma_f32 v1, v1, v161, v177
	v_fma_f32 v2, v2, v162, v178
	v_fma_f32 v3, v3, v163, v179
	v_mul_f32_e32 v4, v4, v33
	v_mul_f32_e32 v5, v5, v33
	v_mul_f32_e32 v6, v6, v33
	v_mul_f32_e32 v7, v7, v33
	v_fma_f32 v4, v4, v164, v180
	v_fma_f32 v5, v5, v165, v181
	v_fma_f32 v6, v6, v166, v182
	v_fma_f32 v7, v7, v167, v183
	v_mul_f32_e32 v8, v8, v33
	v_mul_f32_e32 v9, v9, v33
	v_mul_f32_e32 v10, v10, v33
	v_mul_f32_e32 v11, v11, v33
	v_fma_f32 v8, v8, v168, v184
	v_fma_f32 v9, v9, v169, v185
	v_fma_f32 v10, v10, v170, v186
	v_fma_f32 v11, v11, v171, v187
	v_mul_f32_e32 v12, v12, v33
	v_mul_f32_e32 v13, v13, v33
	v_mul_f32_e32 v14, v14, v33
	v_mul_f32_e32 v15, v15, v33
	v_fma_f32 v12, v12, v172, v188
	v_fma_f32 v13, v13, v173, v189
	v_fma_f32 v14, v14, v174, v190
	v_fma_f32 v15, v15, v175, v191
	global_store_dwordx4 v[238:239], v[0:3], off nt
	global_store_dwordx4 v[238:239], v[4:7], off offset:16 nt
	global_store_dwordx4 v[238:239], v[8:11], off offset:2048 nt
	global_store_dwordx4 v[238:239], v[12:15], off offset:2064 nt
	s_mov_b32 s44, 0x800000
	s_mov_b32 s45, 0
	v_lshl_add_u64 v[238:239], v[238:239], 0, s[44:45]
	s_add_u32 s33, s33, 1
	global_load_dwordx4 v[68:71], v[232:233], off
	global_load_dwordx4 v[72:75], v[232:233], off offset:1024
	global_load_dwordx4 v[76:79], v[234:235], off
	global_load_dwordx4 v[80:83], v[234:235], off offset:1024
	global_load_dwordx2 v[84:85], v[236:237], off
	s_cmp_lt_u32 s33, 28
	s_cselect_b32 s44, s40, 0
	s_cselect_b32 s46, s42, 0
	s_mov_b32 s45, 0
	s_mov_b32 s47, 0
	v_lshl_add_u64 v[232:233], v[232:233], 0, s[44:45]
	v_lshl_add_u64 v[234:235], v[234:235], 0, s[44:45]
	v_lshl_add_u64 v[236:237], v[236:237], 0, s[46:47]
	s_waitcnt vmcnt(18)
	v_lshlrev_b32_e32 v16, 16, v96
	v_and_b32_e32 v17, 0xffff0000, v96
	v_lshlrev_b32_e32 v0, 16, v88
	v_and_b32_e32 v1, 0xffff0000, v88
	v_sub_f32_e32 v16, v16, v104
	v_sub_f32_e32 v17, v17, v104
	v_mul_f32_e32 v16, v16, v105
	v_mul_f32_e32 v17, v17, v105
	v_fma_f32 v16, v16, v128, v144
	v_fma_f32 v17, v17, v129, v145
	v_fma_f32 v0, v16, s14, v0
	v_fma_f32 v1, v17, s14, v1
	v_lshlrev_b32_e32 v18, 16, v97
	v_and_b32_e32 v19, 0xffff0000, v97
	v_lshlrev_b32_e32 v2, 16, v89
	v_and_b32_e32 v3, 0xffff0000, v89
	v_sub_f32_e32 v18, v18, v104
	v_sub_f32_e32 v19, v19, v104
	v_mul_f32_e32 v18, v18, v105
	v_mul_f32_e32 v19, v19, v105
	v_fma_f32 v18, v18, v130, v146
	v_fma_f32 v19, v19, v131, v147
	v_fma_f32 v2, v18, s14, v2
	v_fma_f32 v3, v19, s14, v3
	v_lshlrev_b32_e32 v20, 16, v98
	v_and_b32_e32 v21, 0xffff0000, v98
	v_lshlrev_b32_e32 v4, 16, v90
	v_and_b32_e32 v5, 0xffff0000, v90
	v_sub_f32_e32 v20, v20, v104
	v_sub_f32_e32 v21, v21, v104
	v_mul_f32_e32 v20, v20, v105
	v_mul_f32_e32 v21, v21, v105
	v_fma_f32 v20, v20, v132, v148
	v_fma_f32 v21, v21, v133, v149
	v_fma_f32 v4, v20, s14, v4
	v_fma_f32 v5, v21, s14, v5
	v_lshlrev_b32_e32 v22, 16, v99
	v_and_b32_e32 v23, 0xffff0000, v99
	v_lshlrev_b32_e32 v6, 16, v91
	v_and_b32_e32 v7, 0xffff0000, v91
	v_sub_f32_e32 v22, v22, v104
	v_sub_f32_e32 v23, v23, v104
	v_mul_f32_e32 v22, v22, v105
	v_mul_f32_e32 v23, v23, v105
	v_fma_f32 v22, v22, v134, v150
	v_fma_f32 v23, v23, v135, v151
	v_fma_f32 v6, v22, s14, v6
	v_fma_f32 v7, v23, s14, v7
	v_lshlrev_b32_e32 v24, 16, v100
	v_and_b32_e32 v25, 0xffff0000, v100
	v_lshlrev_b32_e32 v8, 16, v92
	v_and_b32_e32 v9, 0xffff0000, v92
	v_sub_f32_e32 v24, v24, v104
	v_sub_f32_e32 v25, v25, v104
	v_mul_f32_e32 v24, v24, v105
	v_mul_f32_e32 v25, v25, v105
	v_fma_f32 v24, v24, v136, v152
	v_fma_f32 v25, v25, v137, v153
	v_fma_f32 v8, v24, s14, v8
	v_fma_f32 v9, v25, s14, v9
	v_lshlrev_b32_e32 v26, 16, v101
	v_and_b32_e32 v27, 0xffff0000, v101
	v_lshlrev_b32_e32 v10, 16, v93
	v_and_b32_e32 v11, 0xffff0000, v93
	v_sub_f32_e32 v26, v26, v104
	v_sub_f32_e32 v27, v27, v104
	v_mul_f32_e32 v26, v26, v105
	v_mul_f32_e32 v27, v27, v105
	v_fma_f32 v26, v26, v138, v154
	v_fma_f32 v27, v27, v139, v155
	v_fma_f32 v10, v26, s14, v10
	v_fma_f32 v11, v27, s14, v11
	v_lshlrev_b32_e32 v28, 16, v102
	v_and_b32_e32 v29, 0xffff0000, v102
	v_lshlrev_b32_e32 v12, 16, v94
	v_and_b32_e32 v13, 0xffff0000, v94
	v_sub_f32_e32 v28, v28, v104
	v_sub_f32_e32 v29, v29, v104
	v_mul_f32_e32 v28, v28, v105
	v_mul_f32_e32 v29, v29, v105
	v_fma_f32 v28, v28, v140, v156
	v_fma_f32 v29, v29, v141, v157
	v_fma_f32 v12, v28, s14, v12
	v_fma_f32 v13, v29, s14, v13
	v_lshlrev_b32_e32 v30, 16, v103
	v_and_b32_e32 v31, 0xffff0000, v103
	v_lshlrev_b32_e32 v14, 16, v95
	v_and_b32_e32 v15, 0xffff0000, v95
	v_sub_f32_e32 v30, v30, v104
	v_sub_f32_e32 v31, v31, v104
	v_mul_f32_e32 v30, v30, v105
	v_mul_f32_e32 v31, v31, v105
	v_fma_f32 v30, v30, v142, v158
	v_fma_f32 v31, v31, v143, v159
	v_fma_f32 v14, v30, s14, v14
	v_fma_f32 v15, v31, s14, v15
	v_add_f32_e32 v16, v0, v1
	v_add_f32_e32 v17, v2, v3
	v_add_f32_e32 v18, v4, v5
	v_add_f32_e32 v19, v6, v7
	v_add_f32_e32 v20, v8, v9
	v_add_f32_e32 v21, v10, v11
	v_add_f32_e32 v22, v12, v13
	v_add_f32_e32 v23, v14, v15
	v_add_f32_e32 v16, v16, v17
	v_add_f32_e32 v18, v18, v19
	v_add_f32_e32 v20, v20, v21
	v_add_f32_e32 v22, v22, v23
	v_add_f32_e32 v16, v16, v18
	v_add_f32_e32 v20, v20, v22
	v_add_f32_e32 v32, v16, v20
	v_mov_b32_e32 v34, v32
	s_nop 1
	v_add_f32_dpp v34, v32, v32 quad_perm:[1,0,3,2] row_mask:0xf bank_mask:0xf
	s_nop 1
	v_add_f32_dpp v34, v34, v34 quad_perm:[2,3,0,1] row_mask:0xf bank_mask:0xf
	s_nop 1
	v_add_f32_dpp v34, v34, v34 row_half_mirror row_mask:0xf bank_mask:0xf
	s_nop 1
	v_add_f32_dpp v34, v34, v34 row_mirror row_mask:0xf bank_mask:0xf
	s_nop 1
	v_add_f32_dpp v34, v34, v34 row_bcast:15 row_mask:0xa bank_mask:0xf
	s_nop 1
	v_add_f32_dpp v34, v34, v34 row_bcast:31 row_mask:0xc bank_mask:0xf
	s_nop 1
	v_readlane_b32 s0, v34, 63
	s_nop 0
	v_mov_b32_e32 v33, 0x3a800000
	v_mul_f32_e32 v33, s0, v33
	v_sub_f32_e32 v0, v0, v33
	v_sub_f32_e32 v1, v1, v33
	v_sub_f32_e32 v2, v2, v33
	v_sub_f32_e32 v3, v3, v33
	v_sub_f32_e32 v4, v4, v33
	v_sub_f32_e32 v5, v5, v33
	v_sub_f32_e32 v6, v6, v33
	v_sub_f32_e32 v7, v7, v33
	v_sub_f32_e32 v8, v8, v33
	v_sub_f32_e32 v9, v9, v33
	v_sub_f32_e32 v10, v10, v33
	v_sub_f32_e32 v11, v11, v33
	v_sub_f32_e32 v12, v12, v33
	v_sub_f32_e32 v13, v13, v33
	v_sub_f32_e32 v14, v14, v33
	v_sub_f32_e32 v15, v15, v33
	v_mul_f32_e32 v16, v0, v0
	v_fmac_f32_e32 v16, v1, v1
	v_mul_f32_e32 v17, v2, v2
	v_fmac_f32_e32 v17, v3, v3
	v_mul_f32_e32 v18, v4, v4
	v_fmac_f32_e32 v18, v5, v5
	v_mul_f32_e32 v19, v6, v6
	v_fmac_f32_e32 v19, v7, v7
	v_mul_f32_e32 v20, v8, v8
	v_fmac_f32_e32 v20, v9, v9
	v_mul_f32_e32 v21, v10, v10
	v_fmac_f32_e32 v21, v11, v11
	v_mul_f32_e32 v22, v12, v12
	v_fmac_f32_e32 v22, v13, v13
	v_mul_f32_e32 v23, v14, v14
	v_fmac_f32_e32 v23, v15, v15
	v_add_f32_e32 v16, v16, v17
	v_add_f32_e32 v18, v18, v19
	v_add_f32_e32 v20, v20, v21
	v_add_f32_e32 v22, v22, v23
	v_add_f32_e32 v16, v16, v18
	v_add_f32_e32 v20, v20, v22
	v_add_f32_e32 v32, v16, v20
	v_mov_b32_e32 v34, v32
	s_nop 1
	v_add_f32_dpp v34, v32, v32 quad_perm:[1,0,3,2] row_mask:0xf bank_mask:0xf
	s_nop 1
	v_add_f32_dpp v34, v34, v34 quad_perm:[2,3,0,1] row_mask:0xf bank_mask:0xf
	s_nop 1
	v_add_f32_dpp v34, v34, v34 row_half_mirror row_mask:0xf bank_mask:0xf
	s_nop 1
	v_add_f32_dpp v34, v34, v34 row_mirror row_mask:0xf bank_mask:0xf
	s_nop 1
	v_add_f32_dpp v34, v34, v34 row_bcast:15 row_mask:0xa bank_mask:0xf
	s_nop 1
	v_add_f32_dpp v34, v34, v34 row_bcast:31 row_mask:0xc bank_mask:0xf
	s_nop 1
	v_readlane_b32 s0, v34, 63
	s_nop 0
	v_mov_b32_e32 v33, 0x3a800000
	v_mov_b32_e32 v35, 0x3727c5ac
	v_fma_f32 v33, s0, v33, v35
	v_rsq_f32_e32 v33, v33
	s_nop 0
	v_mul_f32_e32 v0, v0, v33
	v_mul_f32_e32 v1, v1, v33
	v_mul_f32_e32 v2, v2, v33
	v_mul_f32_e32 v3, v3, v33
	v_fma_f32 v0, v0, v160, v176
	v_fma_f32 v1, v1, v161, v177
	v_fma_f32 v2, v2, v162, v178
	v_fma_f32 v3, v3, v163, v179
	v_mul_f32_e32 v4, v4, v33
	v_mul_f32_e32 v5, v5, v33
	v_mul_f32_e32 v6, v6, v33
	v_mul_f32_e32 v7, v7, v33
	v_fma_f32 v4, v4, v164, v180
	v_fma_f32 v5, v5, v165, v181
	v_fma_f32 v6, v6, v166, v182
	v_fma_f32 v7, v7, v167, v183
	v_mul_f32_e32 v8, v8, v33
	v_mul_f32_e32 v9, v9, v33
	v_mul_f32_e32 v10, v10, v33
	v_mul_f32_e32 v11, v11, v33
	v_fma_f32 v8, v8, v168, v184
	v_fma_f32 v9, v9, v169, v185
	v_fma_f32 v10, v10, v170, v186
	v_fma_f32 v11, v11, v171, v187
	v_mul_f32_e32 v12, v12, v33
	v_mul_f32_e32 v13, v13, v33
	v_mul_f32_e32 v14, v14, v33
	v_mul_f32_e32 v15, v15, v33
	v_fma_f32 v12, v12, v172, v188
	v_fma_f32 v13, v13, v173, v189
	v_fma_f32 v14, v14, v174, v190
	v_fma_f32 v15, v15, v175, v191
	global_store_dwordx4 v[238:239], v[0:3], off nt
	global_store_dwordx4 v[238:239], v[4:7], off offset:16 nt
	global_store_dwordx4 v[238:239], v[8:11], off offset:2048 nt
	global_store_dwordx4 v[238:239], v[12:15], off offset:2064 nt
	s_mov_b32 s44, 0x800000
	s_mov_b32 s45, 0
	v_lshl_add_u64 v[238:239], v[238:239], 0, s[44:45]
	s_add_u32 s33, s33, 1
	global_load_dwordx4 v[88:91], v[232:233], off
	global_load_dwordx4 v[92:95], v[232:233], off offset:1024
	global_load_dwordx4 v[96:99], v[234:235], off
	global_load_dwordx4 v[100:103], v[234:235], off offset:1024
	global_load_dwordx2 v[104:105], v[236:237], off
	s_cmp_lt_u32 s33, 28
	s_cselect_b32 s44, s40, 0
	s_cselect_b32 s46, s42, 0
	s_mov_b32 s45, 0
	s_mov_b32 s47, 0
	v_lshl_add_u64 v[232:233], v[232:233], 0, s[44:45]
	v_lshl_add_u64 v[234:235], v[234:235], 0, s[44:45]
	v_lshl_add_u64 v[236:237], v[236:237], 0, s[46:47]
	s_waitcnt vmcnt(18)
	v_lshlrev_b32_e32 v16, 16, v116
	v_and_b32_e32 v17, 0xffff0000, v116
	v_lshlrev_b32_e32 v0, 16, v108
	v_and_b32_e32 v1, 0xffff0000, v108
	v_sub_f32_e32 v16, v16, v124
	v_sub_f32_e32 v17, v17, v124
	v_mul_f32_e32 v16, v16, v125
	v_mul_f32_e32 v17, v17, v125
	v_fma_f32 v16, v16, v128, v144
	v_fma_f32 v17, v17, v129, v145
	v_fma_f32 v0, v16, s14, v0
	v_fma_f32 v1, v17, s14, v1
	v_lshlrev_b32_e32 v18, 16, v117
	v_and_b32_e32 v19, 0xffff0000, v117
	v_lshlrev_b32_e32 v2, 16, v109
	v_and_b32_e32 v3, 0xffff0000, v109
	v_sub_f32_e32 v18, v18, v124
	v_sub_f32_e32 v19, v19, v124
	v_mul_f32_e32 v18, v18, v125
	v_mul_f32_e32 v19, v19, v125
	v_fma_f32 v18, v18, v130, v146
	v_fma_f32 v19, v19, v131, v147
	v_fma_f32 v2, v18, s14, v2
	v_fma_f32 v3, v19, s14, v3
	v_lshlrev_b32_e32 v20, 16, v118
	v_and_b32_e32 v21, 0xffff0000, v118
	v_lshlrev_b32_e32 v4, 16, v110
	v_and_b32_e32 v5, 0xffff0000, v110
	v_sub_f32_e32 v20, v20, v124
	v_sub_f32_e32 v21, v21, v124
	v_mul_f32_e32 v20, v20, v125
	v_mul_f32_e32 v21, v21, v125
	v_fma_f32 v20, v20, v132, v148
	v_fma_f32 v21, v21, v133, v149
	v_fma_f32 v4, v20, s14, v4
	v_fma_f32 v5, v21, s14, v5
	v_lshlrev_b32_e32 v22, 16, v119
	v_and_b32_e32 v23, 0xffff0000, v119
	v_lshlrev_b32_e32 v6, 16, v111
	v_and_b32_e32 v7, 0xffff0000, v111
	v_sub_f32_e32 v22, v22, v124
	v_sub_f32_e32 v23, v23, v124
	v_mul_f32_e32 v22, v22, v125
	v_mul_f32_e32 v23, v23, v125
	v_fma_f32 v22, v22, v134, v150
	v_fma_f32 v23, v23, v135, v151
	v_fma_f32 v6, v22, s14, v6
	v_fma_f32 v7, v23, s14, v7
	v_lshlrev_b32_e32 v24, 16, v120
	v_and_b32_e32 v25, 0xffff0000, v120
	v_lshlrev_b32_e32 v8, 16, v112
	v_and_b32_e32 v9, 0xffff0000, v112
	v_sub_f32_e32 v24, v24, v124
	v_sub_f32_e32 v25, v25, v124
	v_mul_f32_e32 v24, v24, v125
	v_mul_f32_e32 v25, v25, v125
	v_fma_f32 v24, v24, v136, v152
	v_fma_f32 v25, v25, v137, v153
	v_fma_f32 v8, v24, s14, v8
	v_fma_f32 v9, v25, s14, v9
	v_lshlrev_b32_e32 v26, 16, v121
	v_and_b32_e32 v27, 0xffff0000, v121
	v_lshlrev_b32_e32 v10, 16, v113
	v_and_b32_e32 v11, 0xffff0000, v113
	v_sub_f32_e32 v26, v26, v124
	v_sub_f32_e32 v27, v27, v124
	v_mul_f32_e32 v26, v26, v125
	v_mul_f32_e32 v27, v27, v125
	v_fma_f32 v26, v26, v138, v154
	v_fma_f32 v27, v27, v139, v155
	v_fma_f32 v10, v26, s14, v10
	v_fma_f32 v11, v27, s14, v11
	v_lshlrev_b32_e32 v28, 16, v122
	v_and_b32_e32 v29, 0xffff0000, v122
	v_lshlrev_b32_e32 v12, 16, v114
	v_and_b32_e32 v13, 0xffff0000, v114
	v_sub_f32_e32 v28, v28, v124
	v_sub_f32_e32 v29, v29, v124
	v_mul_f32_e32 v28, v28, v125
	v_mul_f32_e32 v29, v29, v125
	v_fma_f32 v28, v28, v140, v156
	v_fma_f32 v29, v29, v141, v157
	v_fma_f32 v12, v28, s14, v12
	v_fma_f32 v13, v29, s14, v13
	v_lshlrev_b32_e32 v30, 16, v123
	v_and_b32_e32 v31, 0xffff0000, v123
	v_lshlrev_b32_e32 v14, 16, v115
	v_and_b32_e32 v15, 0xffff0000, v115
	v_sub_f32_e32 v30, v30, v124
	v_sub_f32_e32 v31, v31, v124
	v_mul_f32_e32 v30, v30, v125
	v_mul_f32_e32 v31, v31, v125
	v_fma_f32 v30, v30, v142, v158
	v_fma_f32 v31, v31, v143, v159
	v_fma_f32 v14, v30, s14, v14
	v_fma_f32 v15, v31, s14, v15
	v_add_f32_e32 v16, v0, v1
	v_add_f32_e32 v17, v2, v3
	v_add_f32_e32 v18, v4, v5
	v_add_f32_e32 v19, v6, v7
	v_add_f32_e32 v20, v8, v9
	v_add_f32_e32 v21, v10, v11
	v_add_f32_e32 v22, v12, v13
	v_add_f32_e32 v23, v14, v15
	v_add_f32_e32 v16, v16, v17
	v_add_f32_e32 v18, v18, v19
	v_add_f32_e32 v20, v20, v21
	v_add_f32_e32 v22, v22, v23
	v_add_f32_e32 v16, v16, v18
	v_add_f32_e32 v20, v20, v22
	v_add_f32_e32 v32, v16, v20
	v_mov_b32_e32 v34, v32
	s_nop 1
	v_add_f32_dpp v34, v32, v32 quad_perm:[1,0,3,2] row_mask:0xf bank_mask:0xf
	s_nop 1
	v_add_f32_dpp v34, v34, v34 quad_perm:[2,3,0,1] row_mask:0xf bank_mask:0xf
	s_nop 1
	v_add_f32_dpp v34, v34, v34 row_half_mirror row_mask:0xf bank_mask:0xf
	s_nop 1
	v_add_f32_dpp v34, v34, v34 row_mirror row_mask:0xf bank_mask:0xf
	s_nop 1
	v_add_f32_dpp v34, v34, v34 row_bcast:15 row_mask:0xa bank_mask:0xf
	s_nop 1
	v_add_f32_dpp v34, v34, v34 row_bcast:31 row_mask:0xc bank_mask:0xf
	s_nop 1
	v_readlane_b32 s0, v34, 63
	s_nop 0
	v_mov_b32_e32 v33, 0x3a800000
	v_mul_f32_e32 v33, s0, v33
	v_sub_f32_e32 v0, v0, v33
	v_sub_f32_e32 v1, v1, v33
	v_sub_f32_e32 v2, v2, v33
	v_sub_f32_e32 v3, v3, v33
	v_sub_f32_e32 v4, v4, v33
	v_sub_f32_e32 v5, v5, v33
	v_sub_f32_e32 v6, v6, v33
	v_sub_f32_e32 v7, v7, v33
	v_sub_f32_e32 v8, v8, v33
	v_sub_f32_e32 v9, v9, v33
	v_sub_f32_e32 v10, v10, v33
	v_sub_f32_e32 v11, v11, v33
	v_sub_f32_e32 v12, v12, v33
	v_sub_f32_e32 v13, v13, v33
	v_sub_f32_e32 v14, v14, v33
	v_sub_f32_e32 v15, v15, v33
	v_mul_f32_e32 v16, v0, v0
	v_fmac_f32_e32 v16, v1, v1
	v_mul_f32_e32 v17, v2, v2
	v_fmac_f32_e32 v17, v3, v3
	v_mul_f32_e32 v18, v4, v4
	v_fmac_f32_e32 v18, v5, v5
	v_mul_f32_e32 v19, v6, v6
	v_fmac_f32_e32 v19, v7, v7
	v_mul_f32_e32 v20, v8, v8
	v_fmac_f32_e32 v20, v9, v9
	v_mul_f32_e32 v21, v10, v10
	v_fmac_f32_e32 v21, v11, v11
	v_mul_f32_e32 v22, v12, v12
	v_fmac_f32_e32 v22, v13, v13
	v_mul_f32_e32 v23, v14, v14
	v_fmac_f32_e32 v23, v15, v15
	v_add_f32_e32 v16, v16, v17
	v_add_f32_e32 v18, v18, v19
	v_add_f32_e32 v20, v20, v21
	v_add_f32_e32 v22, v22, v23
	v_add_f32_e32 v16, v16, v18
	v_add_f32_e32 v20, v20, v22
	v_add_f32_e32 v32, v16, v20
	v_mov_b32_e32 v34, v32
	s_nop 1
	v_add_f32_dpp v34, v32, v32 quad_perm:[1,0,3,2] row_mask:0xf bank_mask:0xf
	s_nop 1
	v_add_f32_dpp v34, v34, v34 quad_perm:[2,3,0,1] row_mask:0xf bank_mask:0xf
	s_nop 1
	v_add_f32_dpp v34, v34, v34 row_half_mirror row_mask:0xf bank_mask:0xf
	s_nop 1
	v_add_f32_dpp v34, v34, v34 row_mirror row_mask:0xf bank_mask:0xf
	s_nop 1
	v_add_f32_dpp v34, v34, v34 row_bcast:15 row_mask:0xa bank_mask:0xf
	s_nop 1
	v_add_f32_dpp v34, v34, v34 row_bcast:31 row_mask:0xc bank_mask:0xf
	s_nop 1
	v_readlane_b32 s0, v34, 63
	s_nop 0
	v_mov_b32_e32 v33, 0x3a800000
	v_mov_b32_e32 v35, 0x3727c5ac
	v_fma_f32 v33, s0, v33, v35
	v_rsq_f32_e32 v33, v33
	s_nop 0
	v_mul_f32_e32 v0, v0, v33
	v_mul_f32_e32 v1, v1, v33
	v_mul_f32_e32 v2, v2, v33
	v_mul_f32_e32 v3, v3, v33
	v_fma_f32 v0, v0, v160, v176
	v_fma_f32 v1, v1, v161, v177
	v_fma_f32 v2, v2, v162, v178
	v_fma_f32 v3, v3, v163, v179
	v_mul_f32_e32 v4, v4, v33
	v_mul_f32_e32 v5, v5, v33
	v_mul_f32_e32 v6, v6, v33
	v_mul_f32_e32 v7, v7, v33
	v_fma_f32 v4, v4, v164, v180
	v_fma_f32 v5, v5, v165, v181
	v_fma_f32 v6, v6, v166, v182
	v_fma_f32 v7, v7, v167, v183
	v_mul_f32_e32 v8, v8, v33
	v_mul_f32_e32 v9, v9, v33
	v_mul_f32_e32 v10, v10, v33
	v_mul_f32_e32 v11, v11, v33
	v_fma_f32 v8, v8, v168, v184
	v_fma_f32 v9, v9, v169, v185
	v_fma_f32 v10, v10, v170, v186
	v_fma_f32 v11, v11, v171, v187
	v_mul_f32_e32 v12, v12, v33
	v_mul_f32_e32 v13, v13, v33
	v_mul_f32_e32 v14, v14, v33
	v_mul_f32_e32 v15, v15, v33
	v_fma_f32 v12, v12, v172, v188
	v_fma_f32 v13, v13, v173, v189
	v_fma_f32 v14, v14, v174, v190
	v_fma_f32 v15, v15, v175, v191
	global_store_dwordx4 v[238:239], v[0:3], off nt
	global_store_dwordx4 v[238:239], v[4:7], off offset:16 nt
	global_store_dwordx4 v[238:239], v[8:11], off offset:2048 nt
	global_store_dwordx4 v[238:239], v[12:15], off offset:2064 nt
	s_mov_b32 s44, 0x800000
	s_mov_b32 s45, 0
	v_lshl_add_u64 v[238:239], v[238:239], 0, s[44:45]
	s_add_u32 s33, s33, 1
	s_cmp_lt_u32 s33, 32
	s_cbranch_scc1 .Lln2_loop
	s_endpgm
